# PEER gate softmax denominators via DPP wave reduction + readlane instead of 4 dependent ds_bpermute levels per head
# speedup vs baseline: 1.0123x; 1.0051x over previous
.LBB0_328:
	v_ashrrev_i32_e32 v117, 31, v116
	v_lshlrev_b64 v[0:1], 11, v[116:117]
	v_lshl_add_u64 v[134:135], v[122:123], 0, v[0:1]
	global_load_dwordx4 v[12:15], v[134:135], off
	global_load_dwordx4 v[0:3], v[134:135], off offset:16
	v_readlane_b32 s2, v249, 30
	v_readlane_b32 s3, v249, 31
	s_load_dwordx2 s[2:3], s[2:3], 0x180
	v_lshlrev_b64 v[136:137], 10, v[116:117]
	v_mov_b32_e32 v131, v80
	v_mov_b32_e32 v133, v80
	s_movk_i32 s43, 0x80
	s_waitcnt lgkmcnt(0)
	v_lshl_add_u64 v[4:5], s[2:3], 0, v[136:137]
	v_lshl_add_u64 v[4:5], s[58:59], 0, v[4:5]
	v_lshl_add_u64 v[18:19], v[4:5], 0, v[130:131]
	v_lshl_add_u64 v[16:17], v[4:5], 0, v[132:133]
	global_load_dword v26, v[16:17], off offset:64
	global_load_dword v28, v[18:19], off
	global_load_dword v25, v[16:17], off offset:192
	global_load_dword v27, v[18:19], off offset:128
	global_load_dwordx4 v[4:7], v[134:135], off offset:48
	global_load_dwordx4 v[8:11], v[134:135], off offset:32
	global_load_dword v21, v[18:19], off offset:256
	global_load_dword v23, v[18:19], off offset:384
	global_load_dword v22, v[18:19], off offset:512
	global_load_dword v24, v[18:19], off offset:640
	global_load_dword v20, v[18:19], off offset:768
	s_nop 0
	global_load_dword v18, v[18:19], off offset:896
	s_nop 0
	global_load_dword v117, v[16:17], off offset:320
	global_load_dword v31, v[16:17], off offset:448
	global_load_dword v30, v[16:17], off offset:576
	global_load_dword v29, v[16:17], off offset:704
	global_load_dword v19, v[16:17], off offset:832
	s_nop 0
	global_load_dword v16, v[16:17], off offset:960
	s_movk_i32 s44, 0x3f80
	v_mov_b32_e32 v176, 0
	v_mov_b32_e32 v177, v176
	v_mov_b32_e32 v216, v176
	v_mov_b32_e32 v217, v176
	v_mov_b32_e32 v214, v176
	v_mov_b32_e32 v215, v176
	v_mov_b32_e32 v212, v176
	v_mov_b32_e32 v213, v176
	v_mov_b32_e32 v210, v176
	v_mov_b32_e32 v211, v176
	v_mov_b32_e32 v208, v176
	v_mov_b32_e32 v209, v176
	v_mov_b32_e32 v206, v176
	v_mov_b32_e32 v207, v176
	v_mov_b32_e32 v204, v176
	v_mov_b32_e32 v205, v176
	v_mov_b32_e32 v202, v176
	v_mov_b32_e32 v203, v176
	v_mov_b32_e32 v200, v176
	v_mov_b32_e32 v201, v176
	v_mov_b32_e32 v198, v176
	v_mov_b32_e32 v199, v176
	v_mov_b32_e32 v196, v176
	v_mov_b32_e32 v197, v176
	v_mov_b32_e32 v194, v176
	v_mov_b32_e32 v195, v176
	v_mov_b32_e32 v192, v176
	v_mov_b32_e32 v193, v176
	v_mov_b32_e32 v190, v176
	v_mov_b32_e32 v191, v176
	v_mov_b32_e32 v188, v176
	v_mov_b32_e32 v189, v176
	s_waitcnt vmcnt(17)
	v_cmp_lt_i32_e32 vcc, -1, v26
	s_waitcnt vmcnt(13)
	v_lshlrev_b32_e32 v160, 16, v4
	v_lshlrev_b32_e32 v152, 16, v12
	v_lshlrev_b32_e32 v174, 16, v1
	v_and_b32_e32 v143, 0xffff0000, v1
	v_cndmask_b32_e64 v1, v232, -1, vcc
	v_cmp_lt_i32_e32 vcc, -1, v28
	v_and_b32_e32 v150, 0xffff0000, v12
	v_lshlrev_b32_e32 v148, 16, v14
	v_cndmask_b32_e64 v12, v232, -1, vcc
	v_cmp_lt_i32_e32 vcc, -1, v25
	v_and_b32_e32 v146, 0xffff0000, v14
	v_lshlrev_b32_e32 v172, 16, v15
	v_cndmask_b32_e64 v17, v232, -1, vcc
	v_cmp_lt_i32_e32 vcc, -1, v27
	v_and_b32_e32 v147, 0xffff0000, v15
	v_lshlrev_b32_e32 v144, 16, v0
	v_and_b32_e32 v142, 0xffff0000, v0
	v_lshlrev_b32_e32 v140, 16, v2
	v_and_b32_e32 v138, 0xffff0000, v2
	v_and_b32_e32 v0, 0xffffff80, v26
	v_and_b32_e32 v2, 0xffffff80, v28
	v_and_b32_e32 v14, 0xffffff80, v25
	v_and_b32_e32 v15, 0xffffff80, v27
	v_cndmask_b32_e64 v32, v232, -1, vcc
	v_lshlrev_b32_e32 v170, 16, v13
	v_and_b32_e32 v151, 0xffff0000, v13
	v_xor_b32_e32 v1, v1, v0
	v_xor_b32_e32 v13, v12, v2
	v_xor_b32_e32 v0, v17, v14
	v_xor_b32_e32 v12, v32, v15
	v_pk_add_f32 v[0:1], v[12:13], v[0:1]
	v_lshlrev_b32_e32 v178, 16, v3
	v_or_b32_e32 v2, 0x80000000, v1
	v_not_b32_e32 v12, v1
	v_cmp_gt_i32_e32 vcc, 0, v1
	v_and_b32_e32 v139, 0xffff0000, v3
	s_waitcnt vmcnt(12)
	v_lshlrev_b32_e32 v168, 16, v8
	v_cndmask_b32_e32 v2, v2, v12, vcc
	v_and_b32_e32 v2, 0xffffffc0, v2
	v_bitop3_b32 v2, v2, 63, v81 bitop3:0x36
	v_cndmask_b32_e64 v2, 0, v2, s[10:11]
	v_and_b32_e32 v166, 0xffff0000, v8
	v_readlane_b32 s3, v2, 1
	v_readlane_b32 s24, v2, 2
	v_readlane_b32 s26, v2, 4
	v_cmp_gt_u32_e32 vcc, s3, v2
	v_readlane_b32 s30, v2, 6
	v_readlane_b32 s34, v2, 8
	v_cndmask_b32_e64 v12, 0, 1, vcc
	v_cmp_gt_u32_e32 vcc, s24, v2
	v_readlane_b32 s2, v2, 0
	v_readlane_b32 s25, v2, 3
	v_cndmask_b32_e64 v13, 0, 1, vcc
	v_cmp_gt_u32_e32 vcc, s26, v2
	v_readlane_b32 s27, v2, 5
	v_readlane_b32 s31, v2, 7
	v_cndmask_b32_e64 v14, 0, 1, vcc
	v_cmp_gt_u32_e32 vcc, s30, v2
	v_and_b32_e32 v158, 0xffff0000, v4
	v_lshlrev_b32_e32 v184, 16, v5
	v_cndmask_b32_e64 v15, 0, 1, vcc
	v_cmp_gt_u32_e32 vcc, s34, v2
	v_and_b32_e32 v159, 0xffff0000, v5
	v_lshlrev_b32_e32 v156, 16, v6
	v_cndmask_b32_e64 v17, 0, 1, vcc
	v_cmp_gt_u32_e32 vcc, s2, v2
	v_readlane_b32 s2, v2, 9
	v_and_b32_e32 v154, 0xffff0000, v6
	v_addc_co_u32_e32 v12, vcc, 0, v12, vcc
	v_cmp_gt_u32_e32 vcc, s25, v2
	v_lshlrev_b32_e32 v5, 7, v28
	v_and_b32_e32 v6, 0x7f, v26
	v_addc_co_u32_e32 v12, vcc, v12, v13, vcc
	v_cmp_gt_u32_e32 vcc, s27, v2
	v_and_or_b32 v5, v5, s44, v6
	v_lshlrev_b32_e32 v186, 16, v7
	v_addc_co_u32_e32 v12, vcc, v12, v14, vcc
	v_cmp_gt_u32_e32 vcc, s31, v2
	v_and_b32_e32 v155, 0xffff0000, v7
	v_lshlrev_b32_e32 v164, 16, v10
	v_addc_co_u32_e32 v12, vcc, v12, v15, vcc
	v_cmp_gt_u32_e32 vcc, s2, v2
	v_readlane_b32 s2, v2, 10
	v_and_b32_e32 v162, 0xffff0000, v10
	v_addc_co_u32_e32 v12, vcc, v12, v17, vcc
	v_cmp_gt_u32_e32 vcc, s2, v2
	v_readlane_b32 s2, v2, 11
	v_lshlrev_b32_e32 v182, 16, v11
	v_cndmask_b32_e64 v13, 0, 1, vcc
	v_cmp_gt_u32_e32 vcc, s2, v2
	v_readlane_b32 s2, v2, 12
	v_and_b32_e32 v163, 0xffff0000, v11
	v_addc_co_u32_e32 v12, vcc, v12, v13, vcc
	v_cmp_gt_u32_e32 vcc, s2, v2
	v_readlane_b32 s2, v2, 13
	v_not_b32_e32 v17, v0
	v_cndmask_b32_e64 v13, 0, 1, vcc
	v_cmp_gt_u32_e32 vcc, s2, v2
	v_readlane_b32 s2, v2, 14
	v_lshlrev_b32_e32 v180, 16, v9
	v_addc_co_u32_e32 v12, vcc, v12, v13, vcc
	v_cmp_gt_u32_e32 vcc, s2, v2
	v_readlane_b32 s2, v2, 15
	v_and_b32_e32 v167, 0xffff0000, v9
	v_cndmask_b32_e64 v13, 0, 1, vcc
	v_cmp_gt_u32_e32 vcc, s2, v2
	v_readlane_b32 s2, v2, 16
	v_and_b32_e32 v9, 0x7f, v25
	v_addc_co_u32_e32 v12, vcc, v12, v13, vcc
	v_cmp_gt_u32_e32 vcc, s2, v2
	v_readlane_b32 s2, v2, 17
	s_mov_b32 s24, 0
	v_cndmask_b32_e64 v13, 0, 1, vcc
	v_cmp_gt_u32_e32 vcc, s2, v2
	v_readlane_b32 s2, v2, 18
	v_mov_b32_e32 v153, v150
	v_addc_co_u32_e32 v12, vcc, v12, v13, vcc
	v_cmp_gt_u32_e32 vcc, s2, v2
	v_readlane_b32 s2, v2, 19
	v_mov_b32_e32 v171, v151
	v_cndmask_b32_e64 v13, 0, 1, vcc
	v_cmp_gt_u32_e32 vcc, s2, v2
	v_readlane_b32 s2, v2, 20
	v_mov_b32_e32 v149, v146
	v_addc_co_u32_e32 v12, vcc, v12, v13, vcc
	v_cmp_gt_u32_e32 vcc, s2, v2
	v_readlane_b32 s2, v2, 21
	v_mov_b32_e32 v173, v147
	v_cndmask_b32_e64 v13, 0, 1, vcc
	v_cmp_gt_u32_e32 vcc, s2, v2
	v_readlane_b32 s2, v2, 22
	v_mov_b32_e32 v145, v142
	v_addc_co_u32_e32 v12, vcc, v12, v13, vcc
	v_cmp_gt_u32_e32 vcc, s2, v2
	v_readlane_b32 s2, v2, 23
	v_mov_b32_e32 v175, v143
	v_cndmask_b32_e64 v13, 0, 1, vcc
	v_cmp_gt_u32_e32 vcc, s2, v2
	v_readlane_b32 s2, v2, 24
	v_mov_b32_e32 v141, v138
	v_addc_co_u32_e32 v12, vcc, v12, v13, vcc
	v_cmp_gt_u32_e32 vcc, s2, v2
	v_readlane_b32 s2, v2, 25
	v_mov_b32_e32 v179, v139
	v_cndmask_b32_e64 v13, 0, 1, vcc
	v_cmp_gt_u32_e32 vcc, s2, v2
	v_readlane_b32 s2, v2, 26
	v_mov_b32_e32 v169, v166
	v_addc_co_u32_e32 v12, vcc, v12, v13, vcc
	v_cmp_gt_u32_e32 vcc, s2, v2
	v_readlane_b32 s2, v2, 27
	v_mov_b32_e32 v181, v167
	v_cndmask_b32_e64 v13, 0, 1, vcc
	v_cmp_gt_u32_e32 vcc, s2, v2
	v_readlane_b32 s2, v2, 28
	v_mov_b32_e32 v165, v162
	v_addc_co_u32_e32 v12, vcc, v12, v13, vcc
	v_cmp_gt_u32_e32 vcc, s2, v2
	v_readlane_b32 s2, v2, 29
	v_mov_b32_e32 v183, v163
	v_cndmask_b32_e64 v13, 0, 1, vcc
	v_cmp_gt_u32_e32 vcc, s2, v2
	v_readlane_b32 s2, v2, 30
	v_mov_b32_e32 v161, v158
	v_addc_co_u32_e32 v12, vcc, v12, v13, vcc
	v_cmp_gt_u32_e32 vcc, s2, v2
	v_readlane_b32 s2, v2, 31
	v_mov_b32_e32 v185, v159
	v_cndmask_b32_e64 v13, 0, 1, vcc
	v_cmp_gt_u32_e32 vcc, s2, v2
	v_readlane_b32 s2, v2, 32
	v_mov_b32_e32 v157, v154
	v_addc_co_u32_e32 v12, vcc, v12, v13, vcc
	v_cmp_gt_u32_e32 vcc, s2, v2
	v_readlane_b32 s2, v2, 33
	v_mov_b32_e32 v187, v155
	v_cndmask_b32_e64 v13, 0, 1, vcc
	v_cmp_gt_u32_e32 vcc, s2, v2
	v_readlane_b32 s2, v2, 34
	s_nop 0
	v_addc_co_u32_e32 v12, vcc, v12, v13, vcc
	v_cmp_gt_u32_e32 vcc, s2, v2
	v_readlane_b32 s2, v2, 35
	s_nop 0
	v_cndmask_b32_e64 v13, 0, 1, vcc
	v_cmp_gt_u32_e32 vcc, s2, v2
	v_readlane_b32 s2, v2, 36
	s_nop 0
	v_addc_co_u32_e32 v12, vcc, v12, v13, vcc
	v_cmp_gt_u32_e32 vcc, s2, v2
	v_readlane_b32 s2, v2, 37
	s_nop 0
	v_cndmask_b32_e64 v13, 0, 1, vcc
	v_cmp_gt_u32_e32 vcc, s2, v2
	v_readlane_b32 s2, v2, 38
	s_nop 0
	v_addc_co_u32_e32 v12, vcc, v12, v13, vcc
	v_cmp_gt_u32_e32 vcc, s2, v2
	v_readlane_b32 s2, v2, 39
	s_nop 0
	v_cndmask_b32_e64 v13, 0, 1, vcc
	v_cmp_gt_u32_e32 vcc, s2, v2
	v_readlane_b32 s2, v2, 40
	s_nop 0
	v_addc_co_u32_e32 v12, vcc, v12, v13, vcc
	v_cmp_gt_u32_e32 vcc, s2, v2
	v_readlane_b32 s2, v2, 41
	s_nop 0
	v_cndmask_b32_e64 v13, 0, 1, vcc
	v_cmp_gt_u32_e32 vcc, s2, v2
	v_readlane_b32 s2, v2, 42
	s_nop 0
	v_addc_co_u32_e32 v12, vcc, v12, v13, vcc
	v_cmp_gt_u32_e32 vcc, s2, v2
	v_readlane_b32 s2, v2, 43
	s_nop 0
	v_cndmask_b32_e64 v13, 0, 1, vcc
	v_cmp_gt_u32_e32 vcc, s2, v2
	v_readlane_b32 s2, v2, 44
	s_nop 0
	v_addc_co_u32_e32 v12, vcc, v12, v13, vcc
	v_cmp_gt_u32_e32 vcc, s2, v2
	v_readlane_b32 s2, v2, 45
	s_nop 0
	v_cndmask_b32_e64 v13, 0, 1, vcc
	v_cmp_gt_u32_e32 vcc, s2, v2
	v_readlane_b32 s2, v2, 46
	s_nop 0
	v_addc_co_u32_e32 v12, vcc, v12, v13, vcc
	v_cmp_gt_u32_e32 vcc, s2, v2
	v_readlane_b32 s2, v2, 47
	s_nop 0
	v_cndmask_b32_e64 v13, 0, 1, vcc
	v_cmp_gt_u32_e32 vcc, s2, v2
	v_readlane_b32 s2, v2, 48
	s_nop 0
	v_addc_co_u32_e32 v12, vcc, v12, v13, vcc
	v_cmp_gt_u32_e32 vcc, s2, v2
	v_readlane_b32 s2, v2, 49
	s_nop 0
	v_cndmask_b32_e64 v13, 0, 1, vcc
	v_cmp_gt_u32_e32 vcc, s2, v2
	s_nop 1
	v_addc_co_u32_e32 v2, vcc, v12, v13, vcc
	v_lshlrev_b32_e32 v13, 3, v2
	v_lshlrev_b32_e32 v12, 7, v2
	v_and_b32_e32 v13, 0x70, v13
	v_and_or_b32 v12, v12, s43, v13
	v_cmp_gt_u32_e32 vcc, 16, v2
	s_nop 1
	v_cndmask_b32_e32 v2, 4, v12, vcc
	ds_permute_b32 v1, v2, v1
	ds_permute_b32 v2, v2, v5
	s_waitcnt lgkmcnt(1)
	v_readlane_b32 s2, v1, 0
	s_nop 1
	v_subrev_f32_e32 v1, s2, v1
	v_mul_f32_e32 v1, 0x3fb8aa3b, v1
	v_exp_f32_e32 v1, v1
	s_waitcnt lgkmcnt(0)
	v_readlane_b32 s25, v2, 4
	v_readlane_b32 s26, v2, 36
	v_readlane_b32 s27, v2, 8
	v_cndmask_b32_e64 v1, 0, v1, s[12:13]
	s_nop 1
	v_add_f32_dpp v254, v1, v1 quad_perm:[1,0,3,2] row_mask:0xf bank_mask:0xf
	s_nop 1
	v_add_f32_dpp v254, v254, v254 quad_perm:[2,3,0,1] row_mask:0xf bank_mask:0xf
	s_nop 1
	v_add_f32_dpp v254, v254, v254 row_half_mirror row_mask:0xf bank_mask:0xf
	s_nop 1
	v_add_f32_dpp v254, v254, v254 row_mirror row_mask:0xf bank_mask:0xf
	s_nop 1
	v_add_f32_dpp v254, v254, v254 row_bcast:15 row_mask:0xa bank_mask:0xf
	s_nop 1
	v_add_f32_dpp v254, v254, v254 row_bcast:31 row_mask:0xc bank_mask:0xf
	s_nop 1
	v_readlane_b32 s64, v254, 63
	v_readlane_b32 s30, v2, 40
	v_readlane_b32 s31, v2, 12
	v_readlane_b32 s34, v2, 44
	v_readlane_b32 s35, v2, 16
	s_waitcnt lgkmcnt(0)
	v_readlane_b32 s36, v2, 48
	v_readlane_b32 s37, v2, 20
	v_readlane_b32 s38, v2, 52
	v_readlane_b32 s39, v2, 24
	s_waitcnt lgkmcnt(0)
	v_readlane_b32 s40, v2, 56
	v_readlane_b32 s41, v2, 28
	v_readlane_b32 s42, v2, 60
	v_lshlrev_b32_e32 v8, 7, v27
	s_waitcnt lgkmcnt(0)
	v_and_or_b32 v8, v8, s44, v9
	s_waitcnt lgkmcnt(0)
	v_mov_b32_e32 v3, s64
	v_div_scale_f32 v4, s[2:3], v3, v3, v1
	v_rcp_f32_e32 v6, v4
	v_readlane_b32 s2, v2, 0
	v_readlane_b32 s3, v2, 32
	v_fma_f32 v5, -v4, v6, 1.0
	v_fmac_f32_e32 v6, v5, v6
	v_div_scale_f32 v5, vcc, v1, v3, v1
	v_mul_f32_e32 v7, v5, v6
	v_fma_f32 v10, -v4, v7, v5
	v_fmac_f32_e32 v7, v10, v6
	v_fma_f32 v4, -v4, v7, v5
	v_div_fmas_f32 v4, v4, v6, v7
	v_div_fixup_f32 v3, v4, v3, v1
	v_mov_b32_e32 v1, s2
	v_mov_b32_e32 v4, s3
	v_cndmask_b32_e64 v1, v1, v4, s[6:7]
	v_mad_i64_i32 v[4:5], s[2:3], v1, s28, v[118:119]
	global_load_dwordx2 v[36:37], v[4:5], off offset:16
	global_load_dwordx4 v[32:35], v[4:5], off
	v_mov_b32_e32 v4, s25
	v_mov_b32_e32 v5, s26
	v_cndmask_b32_e64 v6, v4, v5, s[6:7]
	v_mad_i64_i32 v[4:5], s[2:3], v6, s28, v[118:119]
	global_load_dwordx2 v[42:43], v[4:5], off offset:16
	global_load_dwordx4 v[38:41], v[4:5], off
	v_mov_b32_e32 v4, s27
	v_mov_b32_e32 v5, s30
	v_cndmask_b32_e64 v10, v4, v5, s[6:7]
	v_mad_i64_i32 v[4:5], s[2:3], v10, s28, v[118:119]
	global_load_dwordx2 v[48:49], v[4:5], off offset:16
	global_load_dwordx4 v[44:47], v[4:5], off
	v_mov_b32_e32 v4, s31
	v_mov_b32_e32 v5, s34
	v_cndmask_b32_e64 v11, v4, v5, s[6:7]
	v_mad_i64_i32 v[4:5], s[2:3], v11, s28, v[118:119]
	global_load_dwordx2 v[54:55], v[4:5], off offset:16
	global_load_dwordx4 v[50:53], v[4:5], off
	v_mov_b32_e32 v4, s35
	v_mov_b32_e32 v5, s36
	v_cndmask_b32_e64 v12, v4, v5, s[6:7]
	v_mad_i64_i32 v[4:5], s[2:3], v12, s28, v[118:119]
	global_load_dwordx2 v[60:61], v[4:5], off offset:16
	global_load_dwordx4 v[56:59], v[4:5], off
	v_mov_b32_e32 v4, s37
	v_mov_b32_e32 v5, s38
	v_cndmask_b32_e64 v13, v4, v5, s[6:7]
	v_mad_i64_i32 v[4:5], s[2:3], v13, s28, v[118:119]
	global_load_dwordx2 v[66:67], v[4:5], off offset:16
	global_load_dwordx4 v[62:65], v[4:5], off
	v_mov_b32_e32 v4, s39
	v_mov_b32_e32 v5, s40
	v_cndmask_b32_e64 v14, v4, v5, s[6:7]
	v_mad_i64_i32 v[4:5], s[2:3], v14, s28, v[118:119]
	global_load_dwordx2 v[72:73], v[4:5], off offset:16
	global_load_dwordx4 v[68:71], v[4:5], off
	v_mov_b32_e32 v4, s41
	v_mov_b32_e32 v5, s42
	v_cndmask_b32_e64 v15, v4, v5, s[6:7]
	v_mad_i64_i32 v[4:5], s[2:3], v15, s28, v[118:119]
	global_load_dwordx2 v[78:79], v[4:5], off offset:16
	global_load_dwordx4 v[74:77], v[4:5], off
	v_mad_i64_i32 v[4:5], s[2:3], v1, s28, v[120:121]
	v_or_b32_e32 v1, 0x80000000, v0
	v_cmp_gt_i32_e32 vcc, 0, v0
	v_mad_i64_i32 v[6:7], s[2:3], v6, s28, v[120:121]
	s_nop 0
	v_cndmask_b32_e32 v1, v1, v17, vcc
	v_and_b32_e32 v1, 0xffffffc0, v1
	v_cndmask_b32_e64 v1, 0, v1, s[10:11]
	v_bitop3_b32 v1, v1, 63, v81 bitop3:0x36
	global_load_dwordx4 v[110:113], v[4:5], off offset:768
	global_load_dwordx4 v[106:109], v[6:7], off offset:768
	s_mov_b32 vcc_lo, 0x55555555
	s_mov_b32 vcc_hi, 0x55555555
	s_mov_b32 s48, 0x33333333
	s_mov_b32 s49, 0x33333333
	v_max_u32_dpp v250, v1, v1 quad_perm:[1,0,3,2] row_mask:0xf bank_mask:0xf
	v_min_u32_dpp v251, v1, v1 quad_perm:[1,0,3,2] row_mask:0xf bank_mask:0xf
	v_cndmask_b32_e32 v17, v251, v250, vcc
	s_nop 1
	v_max_u32_dpp v250, v17, v17 quad_perm:[3,2,1,0] row_mask:0xf bank_mask:0xf
	v_min_u32_dpp v251, v17, v17 quad_perm:[3,2,1,0] row_mask:0xf bank_mask:0xf
	v_cndmask_b32_e64 v1, v251, v250, s[48:49]
	s_nop 1
	v_max_u32_dpp v250, v1, v1 quad_perm:[1,0,3,2] row_mask:0xf bank_mask:0xf
	v_min_u32_dpp v251, v1, v1 quad_perm:[1,0,3,2] row_mask:0xf bank_mask:0xf
	v_cndmask_b32_e32 v17, v251, v250, vcc
	s_nop 1
	v_max_u32_dpp v1, v17, v17 row_half_mirror row_mask:0xf bank_mask:0x5
	v_min_u32_dpp v1, v17, v17 row_half_mirror row_mask:0xf bank_mask:0xa
	s_nop 1
	v_max_u32_dpp v250, v1, v1 quad_perm:[2,3,0,1] row_mask:0xf bank_mask:0xf
	v_min_u32_dpp v251, v1, v1 quad_perm:[2,3,0,1] row_mask:0xf bank_mask:0xf
	v_cndmask_b32_e64 v17, v251, v250, s[48:49]
	s_nop 1
	v_max_u32_dpp v250, v17, v17 quad_perm:[1,0,3,2] row_mask:0xf bank_mask:0xf
	v_min_u32_dpp v251, v17, v17 quad_perm:[1,0,3,2] row_mask:0xf bank_mask:0xf
	v_cndmask_b32_e32 v1, v251, v250, vcc
	s_nop 1
	v_max_u32_dpp v17, v1, v1 row_mirror row_mask:0xf bank_mask:0x3
	v_min_u32_dpp v17, v1, v1 row_mirror row_mask:0xf bank_mask:0xc
	s_nop 1
	v_max_u32_dpp v1, v17, v17 row_ror:12 row_mask:0xf bank_mask:0x5
	v_min_u32_dpp v1, v17, v17 row_ror:4 row_mask:0xf bank_mask:0xa
	s_nop 1
	v_max_u32_dpp v250, v1, v1 quad_perm:[2,3,0,1] row_mask:0xf bank_mask:0xf
	v_min_u32_dpp v251, v1, v1 quad_perm:[2,3,0,1] row_mask:0xf bank_mask:0xf
	v_cndmask_b32_e64 v17, v251, v250, s[48:49]
	s_nop 1
	v_max_u32_dpp v250, v17, v17 quad_perm:[1,0,3,2] row_mask:0xf bank_mask:0xf
	v_min_u32_dpp v251, v17, v17 quad_perm:[1,0,3,2] row_mask:0xf bank_mask:0xf
	v_cndmask_b32_e32 v1, v251, v250, vcc
	ds_swizzle_b32 v252, v1 offset:0x7c1f
	s_waitcnt lgkmcnt(0)
	v_max_u32_dpp v17, v252, v1 quad_perm:[0,1,2,3] row_mask:0x5 bank_mask:0xf
	v_min_u32_dpp v17, v252, v1 quad_perm:[0,1,2,3] row_mask:0xa bank_mask:0xf
	s_nop 1
	v_max_u32_dpp v1, v17, v17 row_ror:8 row_mask:0xf bank_mask:0x3
	v_min_u32_dpp v1, v17, v17 row_ror:8 row_mask:0xf bank_mask:0xc
	s_nop 1
	v_max_u32_dpp v17, v1, v1 row_ror:12 row_mask:0xf bank_mask:0x5
	v_min_u32_dpp v17, v1, v1 row_ror:4 row_mask:0xf bank_mask:0xa
	s_nop 1
	v_max_u32_dpp v250, v17, v17 quad_perm:[2,3,0,1] row_mask:0xf bank_mask:0xf
	v_min_u32_dpp v251, v17, v17 quad_perm:[2,3,0,1] row_mask:0xf bank_mask:0xf
	v_cndmask_b32_e64 v1, v251, v250, s[48:49]
	s_nop 1
	v_max_u32_dpp v250, v1, v1 quad_perm:[1,0,3,2] row_mask:0xf bank_mask:0xf
	v_min_u32_dpp v251, v1, v1 quad_perm:[1,0,3,2] row_mask:0xf bank_mask:0xf
	v_cndmask_b32_e32 v17, v251, v250, vcc
	v_xor_b32_e32 v253, 63, v81
	v_lshlrev_b32_e32 v253, 2, v253
	ds_bpermute_b32 v252, v253, v17
	s_waitcnt lgkmcnt(0)
	v_max_u32_dpp v1, v252, v17 quad_perm:[0,1,2,3] row_mask:0x3 bank_mask:0xf
	v_min_u32_dpp v1, v252, v17 quad_perm:[0,1,2,3] row_mask:0xc bank_mask:0xf
	ds_swizzle_b32 v252, v1 offset:0x401f
	s_waitcnt lgkmcnt(0)
	v_max_u32_dpp v17, v252, v1 quad_perm:[0,1,2,3] row_mask:0x5 bank_mask:0xf
	v_min_u32_dpp v17, v252, v1 quad_perm:[0,1,2,3] row_mask:0xa bank_mask:0xf
	s_nop 1
	v_max_u32_dpp v1, v17, v17 row_ror:8 row_mask:0xf bank_mask:0x3
	v_min_u32_dpp v1, v17, v17 row_ror:8 row_mask:0xf bank_mask:0xc
	s_nop 1
	v_max_u32_dpp v17, v1, v1 row_ror:12 row_mask:0xf bank_mask:0x5
	v_min_u32_dpp v17, v1, v1 row_ror:4 row_mask:0xf bank_mask:0xa
	s_nop 1
	v_max_u32_dpp v250, v17, v17 quad_perm:[2,3,0,1] row_mask:0xf bank_mask:0xf
	v_min_u32_dpp v251, v17, v17 quad_perm:[2,3,0,1] row_mask:0xf bank_mask:0xf
	v_cndmask_b32_e64 v1, v251, v250, s[48:49]
	s_nop 1
	v_max_u32_dpp v250, v1, v1 quad_perm:[1,0,3,2] row_mask:0xf bank_mask:0xf
	v_min_u32_dpp v251, v1, v1 quad_perm:[1,0,3,2] row_mask:0xf bank_mask:0xf
	v_cndmask_b32_e32 v17, v251, v250, vcc
	v_not_b32_e32 v253, v17
	v_and_b32_e32 v253, 63, v253
	v_lshlrev_b32_e32 v253, 2, v253
	ds_permute_b32 v1, v253, v81
	s_waitcnt lgkmcnt(0)
	v_lshlrev_b32_e32 v25, 3, v1
	v_lshlrev_b32_e32 v17, 7, v1
	v_and_b32_e32 v25, 0x70, v25
	v_and_or_b32 v17, v17, s43, v25
	v_cmp_gt_u32_e32 vcc, 16, v1
	s_nop 1
	v_cndmask_b32_e32 v17, 4, v17, vcc
	ds_permute_b32 v25, v17, v0
	v_mad_i64_i32 v[0:1], s[2:3], v10, s28, v[120:121]
	s_waitcnt vmcnt(23)
	v_cmp_lt_i32_e32 vcc, -1, v117
	s_waitcnt lgkmcnt(0)
	v_readlane_b32 s2, v25, 0
	s_nop 1
	v_subrev_f32_e32 v4, s2, v25
	v_mul_f32_e32 v4, 0x3fb8aa3b, v4
	v_exp_f32_e32 v6, v4
	v_mad_i64_i32 v[4:5], s[2:3], v11, s28, v[120:121]
	global_load_dwordx4 v[102:105], v[0:1], off offset:768
	global_load_dwordx4 v[98:101], v[4:5], off offset:768
	v_cndmask_b32_e64 v6, 0, v6, s[12:13]
	s_nop 1
	v_add_f32_dpp v254, v6, v6 quad_perm:[1,0,3,2] row_mask:0xf bank_mask:0xf
	s_nop 1
	v_add_f32_dpp v254, v254, v254 quad_perm:[2,3,0,1] row_mask:0xf bank_mask:0xf
	s_nop 1
	v_add_f32_dpp v254, v254, v254 row_half_mirror row_mask:0xf bank_mask:0xf
	s_nop 1
	v_add_f32_dpp v254, v254, v254 row_mirror row_mask:0xf bank_mask:0xf
	s_nop 1
	v_add_f32_dpp v254, v254, v254 row_bcast:15 row_mask:0xa bank_mask:0xf
	s_nop 1
	v_add_f32_dpp v254, v254, v254 row_bcast:31 row_mask:0xc bank_mask:0xf
	s_nop 1
	v_readlane_b32 s65, v254, 63
	v_mad_i64_i32 v[0:1], s[2:3], v12, s28, v[120:121]
	v_mad_i64_i32 v[4:5], s[2:3], v13, s28, v[120:121]
	s_waitcnt lgkmcnt(0)
	global_load_dwordx4 v[94:97], v[0:1], off offset:768
	global_load_dwordx4 v[90:93], v[4:5], off offset:768
	v_mad_i64_i32 v[0:1], s[2:3], v14, s28, v[120:121]
	v_mad_i64_i32 v[4:5], s[2:3], v15, s28, v[120:121]
	s_waitcnt lgkmcnt(0)
	global_load_dwordx4 v[86:89], v[0:1], off offset:768
	global_load_dwordx4 v[82:85], v[4:5], off offset:768
	v_cndmask_b32_e64 v1, v232, -1, vcc
	v_cmp_lt_i32_e32 vcc, -1, v21
	v_and_b32_e32 v0, 0xffffff80, v117
	s_waitcnt lgkmcnt(0)
	v_cndmask_b32_e64 v5, v232, -1, vcc
	s_waitcnt vmcnt(28)
	v_cmp_lt_i32_e32 vcc, -1, v31
	v_and_b32_e32 v4, 0xffffff80, v21
	v_xor_b32_e32 v1, v1, v0
	v_cndmask_b32_e64 v10, v232, -1, vcc
	v_cmp_lt_i32_e32 vcc, -1, v23
	v_xor_b32_e32 v5, v5, v4
	v_and_b32_e32 v0, 0xffffff80, v31
	v_and_b32_e32 v4, 0xffffff80, v23
	v_cndmask_b32_e64 v11, v232, -1, vcc
	v_xor_b32_e32 v0, v10, v0
	v_xor_b32_e32 v4, v11, v4
	v_pk_add_f32 v[0:1], v[4:5], v[0:1]
	v_or_b32_e32 v4, 0x80000000, v1
	v_not_b32_e32 v5, v1
	v_cmp_gt_i32_e32 vcc, 0, v1
	s_nop 1
	v_cndmask_b32_e32 v4, v4, v5, vcc
	v_and_b32_e32 v4, 0xffffffc0, v4
	v_cndmask_b32_e64 v4, 0, v4, s[10:11]
	v_bitop3_b32 v4, v4, 63, v81 bitop3:0x36
	s_nop 0
	s_mov_b32 vcc_lo, 0x55555555
	s_mov_b32 vcc_hi, 0x55555555
	s_mov_b32 s48, 0x33333333
	s_mov_b32 s49, 0x33333333
	v_max_u32_dpp v250, v4, v4 quad_perm:[1,0,3,2] row_mask:0xf bank_mask:0xf
	v_min_u32_dpp v251, v4, v4 quad_perm:[1,0,3,2] row_mask:0xf bank_mask:0xf
	v_cndmask_b32_e32 v5, v251, v250, vcc
	s_nop 1
	v_max_u32_dpp v250, v5, v5 quad_perm:[3,2,1,0] row_mask:0xf bank_mask:0xf
	v_min_u32_dpp v251, v5, v5 quad_perm:[3,2,1,0] row_mask:0xf bank_mask:0xf
	v_cndmask_b32_e64 v4, v251, v250, s[48:49]
	s_nop 1
	v_max_u32_dpp v250, v4, v4 quad_perm:[1,0,3,2] row_mask:0xf bank_mask:0xf
	v_min_u32_dpp v251, v4, v4 quad_perm:[1,0,3,2] row_mask:0xf bank_mask:0xf
	v_cndmask_b32_e32 v5, v251, v250, vcc
	s_nop 1
	v_max_u32_dpp v4, v5, v5 row_half_mirror row_mask:0xf bank_mask:0x5
	v_min_u32_dpp v4, v5, v5 row_half_mirror row_mask:0xf bank_mask:0xa
	s_nop 1
	v_max_u32_dpp v250, v4, v4 quad_perm:[2,3,0,1] row_mask:0xf bank_mask:0xf
	v_min_u32_dpp v251, v4, v4 quad_perm:[2,3,0,1] row_mask:0xf bank_mask:0xf
	v_cndmask_b32_e64 v5, v251, v250, s[48:49]
	s_nop 1
	v_max_u32_dpp v250, v5, v5 quad_perm:[1,0,3,2] row_mask:0xf bank_mask:0xf
	v_min_u32_dpp v251, v5, v5 quad_perm:[1,0,3,2] row_mask:0xf bank_mask:0xf
	v_cndmask_b32_e32 v4, v251, v250, vcc
	s_nop 1
	v_max_u32_dpp v5, v4, v4 row_mirror row_mask:0xf bank_mask:0x3
	v_min_u32_dpp v5, v4, v4 row_mirror row_mask:0xf bank_mask:0xc
	s_nop 1
	v_max_u32_dpp v4, v5, v5 row_ror:12 row_mask:0xf bank_mask:0x5
	v_min_u32_dpp v4, v5, v5 row_ror:4 row_mask:0xf bank_mask:0xa
	s_nop 1
	v_max_u32_dpp v250, v4, v4 quad_perm:[2,3,0,1] row_mask:0xf bank_mask:0xf
	v_min_u32_dpp v251, v4, v4 quad_perm:[2,3,0,1] row_mask:0xf bank_mask:0xf
	v_cndmask_b32_e64 v5, v251, v250, s[48:49]
	s_nop 1
	v_max_u32_dpp v250, v5, v5 quad_perm:[1,0,3,2] row_mask:0xf bank_mask:0xf
	v_min_u32_dpp v251, v5, v5 quad_perm:[1,0,3,2] row_mask:0xf bank_mask:0xf
	v_cndmask_b32_e32 v4, v251, v250, vcc
	ds_swizzle_b32 v252, v4 offset:0x7c1f
	s_waitcnt lgkmcnt(0)
	v_max_u32_dpp v5, v252, v4 quad_perm:[0,1,2,3] row_mask:0x5 bank_mask:0xf
	v_min_u32_dpp v5, v252, v4 quad_perm:[0,1,2,3] row_mask:0xa bank_mask:0xf
	s_nop 1
	v_max_u32_dpp v4, v5, v5 row_ror:8 row_mask:0xf bank_mask:0x3
	v_min_u32_dpp v4, v5, v5 row_ror:8 row_mask:0xf bank_mask:0xc
	s_nop 1
	v_max_u32_dpp v5, v4, v4 row_ror:12 row_mask:0xf bank_mask:0x5
	v_min_u32_dpp v5, v4, v4 row_ror:4 row_mask:0xf bank_mask:0xa
	s_nop 1
	v_max_u32_dpp v250, v5, v5 quad_perm:[2,3,0,1] row_mask:0xf bank_mask:0xf
	v_min_u32_dpp v251, v5, v5 quad_perm:[2,3,0,1] row_mask:0xf bank_mask:0xf
	v_cndmask_b32_e64 v4, v251, v250, s[48:49]
	s_nop 1
	v_max_u32_dpp v250, v4, v4 quad_perm:[1,0,3,2] row_mask:0xf bank_mask:0xf
	v_min_u32_dpp v251, v4, v4 quad_perm:[1,0,3,2] row_mask:0xf bank_mask:0xf
	v_cndmask_b32_e32 v5, v251, v250, vcc
	v_xor_b32_e32 v253, 63, v81
	v_lshlrev_b32_e32 v253, 2, v253
	ds_bpermute_b32 v252, v253, v5
	s_waitcnt lgkmcnt(0)
	v_max_u32_dpp v4, v252, v5 quad_perm:[0,1,2,3] row_mask:0x3 bank_mask:0xf
	v_min_u32_dpp v4, v252, v5 quad_perm:[0,1,2,3] row_mask:0xc bank_mask:0xf
	ds_swizzle_b32 v252, v4 offset:0x401f
	s_waitcnt lgkmcnt(0)
	v_max_u32_dpp v5, v252, v4 quad_perm:[0,1,2,3] row_mask:0x5 bank_mask:0xf
	v_min_u32_dpp v5, v252, v4 quad_perm:[0,1,2,3] row_mask:0xa bank_mask:0xf
	s_nop 1
	v_max_u32_dpp v4, v5, v5 row_ror:8 row_mask:0xf bank_mask:0x3
	v_min_u32_dpp v4, v5, v5 row_ror:8 row_mask:0xf bank_mask:0xc
	s_nop 1
	v_max_u32_dpp v5, v4, v4 row_ror:12 row_mask:0xf bank_mask:0x5
	v_min_u32_dpp v5, v4, v4 row_ror:4 row_mask:0xf bank_mask:0xa
	s_nop 1
	v_max_u32_dpp v250, v5, v5 quad_perm:[2,3,0,1] row_mask:0xf bank_mask:0xf
	v_min_u32_dpp v251, v5, v5 quad_perm:[2,3,0,1] row_mask:0xf bank_mask:0xf
	v_cndmask_b32_e64 v4, v251, v250, s[48:49]
	s_nop 1
	v_max_u32_dpp v250, v4, v4 quad_perm:[1,0,3,2] row_mask:0xf bank_mask:0xf
	v_min_u32_dpp v251, v4, v4 quad_perm:[1,0,3,2] row_mask:0xf bank_mask:0xf
	v_cndmask_b32_e32 v5, v251, v250, vcc
	v_not_b32_e32 v253, v5
	v_and_b32_e32 v253, 63, v253
	v_lshlrev_b32_e32 v253, 2, v253
	ds_permute_b32 v4, v253, v81
	s_waitcnt lgkmcnt(0)
	v_lshlrev_b32_e32 v10, 3, v4
	v_lshlrev_b32_e32 v5, 7, v4
	v_and_b32_e32 v10, 0x70, v10
	v_and_or_b32 v5, v5, s43, v10
	v_cmp_gt_u32_e32 vcc, 16, v4
	ds_permute_b32 v4, v17, v8
	s_nop 0
	v_cndmask_b32_e32 v10, 4, v5, vcc
	ds_permute_b32 v1, v10, v1
	s_waitcnt lgkmcnt(2)
	v_mov_b32_e32 v5, s65
	v_div_scale_f32 v7, s[2:3], v5, v5, v6
	v_rcp_f32_e32 v9, v7
	s_waitcnt lgkmcnt(0)
	v_readlane_b32 s2, v1, 0
	v_div_scale_f32 v11, vcc, v6, v5, v6
	s_nop 0
	v_subrev_f32_e32 v1, s2, v1
	v_mul_f32_e32 v1, 0x3fb8aa3b, v1
	v_exp_f32_e32 v1, v1
	v_fma_f32 v8, -v7, v9, 1.0
	v_fmac_f32_e32 v9, v8, v9
	v_mul_f32_e32 v12, v11, v9
	v_cndmask_b32_e64 v1, 0, v1, s[12:13]
	s_nop 1
	v_add_f32_dpp v254, v1, v1 quad_perm:[1,0,3,2] row_mask:0xf bank_mask:0xf
	s_nop 1
	v_add_f32_dpp v254, v254, v254 quad_perm:[2,3,0,1] row_mask:0xf bank_mask:0xf
	s_nop 1
	v_add_f32_dpp v254, v254, v254 row_half_mirror row_mask:0xf bank_mask:0xf
	s_nop 1
	v_add_f32_dpp v254, v254, v254 row_mirror row_mask:0xf bank_mask:0xf
	s_nop 1
	v_add_f32_dpp v254, v254, v254 row_bcast:15 row_mask:0xa bank_mask:0xf
	s_nop 1
	v_add_f32_dpp v254, v254, v254 row_bcast:31 row_mask:0xc bank_mask:0xf
	s_nop 1
	v_readlane_b32 s64, v254, 63
	v_fma_f32 v13, -v7, v12, v11
	v_fmac_f32_e32 v12, v13, v9
	v_fma_f32 v7, -v7, v12, v11
	v_div_fmas_f32 v7, v7, v9, v12
	s_waitcnt lgkmcnt(0)
	v_div_fixup_f32 v5, v7, v5, v6
	v_or_b32_e32 v6, 0x80000000, v0
	v_not_b32_e32 v7, v0
	v_cmp_gt_i32_e32 vcc, 0, v0
	s_waitcnt lgkmcnt(0)
	v_cndmask_b32_e32 v6, v6, v7, vcc
	v_and_b32_e32 v6, 0xffffffc0, v6
	v_cndmask_b32_e64 v6, 0, v6, s[10:11]
	v_bitop3_b32 v6, v6, 63, v81 bitop3:0x36
	ds_write2st64_b64 v239, v[2:3], v[4:5] offset1:1
	s_cmp_lg_u32 s54, 0
	s_cbranch_scc1 .Lg_selskip
	s_mov_b32 vcc_lo, 0x55555555
	s_waitcnt lgkmcnt(1)
	s_mov_b32 vcc_hi, 0x55555555
	s_mov_b32 s48, 0x33333333
	s_mov_b32 s49, 0x33333333
	v_lshlrev_b32_e32 v2, 7, v21
	v_max_u32_dpp v250, v6, v6 quad_perm:[1,0,3,2] row_mask:0xf bank_mask:0xf
	v_min_u32_dpp v251, v6, v6 quad_perm:[1,0,3,2] row_mask:0xf bank_mask:0xf
	v_cndmask_b32_e32 v7, v251, v250, vcc
	v_and_b32_e32 v3, 0x7f, v117
	s_nop 1
	v_max_u32_dpp v250, v7, v7 quad_perm:[3,2,1,0] row_mask:0xf bank_mask:0xf
	v_min_u32_dpp v251, v7, v7 quad_perm:[3,2,1,0] row_mask:0xf bank_mask:0xf
	v_and_or_b32 v2, v2, s44, v3
	v_cndmask_b32_e64 v6, v251, v250, s[48:49]
	s_nop 1
	v_max_u32_dpp v250, v6, v6 quad_perm:[1,0,3,2] row_mask:0xf bank_mask:0xf
	s_waitcnt lgkmcnt(0)
	v_min_u32_dpp v251, v6, v6 quad_perm:[1,0,3,2] row_mask:0xf bank_mask:0xf
	v_mov_b32_e32 v3, s64
	v_cndmask_b32_e32 v7, v251, v250, vcc
	s_nop 1
	v_max_u32_dpp v6, v7, v7 row_half_mirror row_mask:0xf bank_mask:0x5
	ds_permute_b32 v2, v10, v2
	v_min_u32_dpp v6, v7, v7 row_half_mirror row_mask:0xf bank_mask:0xa
	s_nop 1
	v_max_u32_dpp v250, v6, v6 quad_perm:[2,3,0,1] row_mask:0xf bank_mask:0xf
	v_min_u32_dpp v251, v6, v6 quad_perm:[2,3,0,1] row_mask:0xf bank_mask:0xf
	v_cndmask_b32_e64 v7, v251, v250, s[48:49]
	s_nop 1
	v_max_u32_dpp v250, v7, v7 quad_perm:[1,0,3,2] row_mask:0xf bank_mask:0xf
	v_min_u32_dpp v251, v7, v7 quad_perm:[1,0,3,2] row_mask:0xf bank_mask:0xf
	v_cndmask_b32_e32 v6, v251, v250, vcc
	s_nop 1
	v_max_u32_dpp v7, v6, v6 row_mirror row_mask:0xf bank_mask:0x3
	v_min_u32_dpp v7, v6, v6 row_mirror row_mask:0xf bank_mask:0xc
	s_nop 1
	v_max_u32_dpp v6, v7, v7 row_ror:12 row_mask:0xf bank_mask:0x5
	v_min_u32_dpp v6, v7, v7 row_ror:4 row_mask:0xf bank_mask:0xa
	s_nop 1
	v_max_u32_dpp v250, v6, v6 quad_perm:[2,3,0,1] row_mask:0xf bank_mask:0xf
	v_min_u32_dpp v251, v6, v6 quad_perm:[2,3,0,1] row_mask:0xf bank_mask:0xf
	v_cndmask_b32_e64 v7, v251, v250, s[48:49]
	s_nop 1
	v_max_u32_dpp v250, v7, v7 quad_perm:[1,0,3,2] row_mask:0xf bank_mask:0xf
	v_min_u32_dpp v251, v7, v7 quad_perm:[1,0,3,2] row_mask:0xf bank_mask:0xf
	v_cndmask_b32_e32 v6, v251, v250, vcc
	ds_swizzle_b32 v252, v6 offset:0x7c1f
	s_waitcnt lgkmcnt(0)
	v_max_u32_dpp v7, v252, v6 quad_perm:[0,1,2,3] row_mask:0x5 bank_mask:0xf
	v_min_u32_dpp v7, v252, v6 quad_perm:[0,1,2,3] row_mask:0xa bank_mask:0xf
	s_nop 1
	v_max_u32_dpp v6, v7, v7 row_ror:8 row_mask:0xf bank_mask:0x3
	v_min_u32_dpp v6, v7, v7 row_ror:8 row_mask:0xf bank_mask:0xc
	s_nop 1
	v_max_u32_dpp v7, v6, v6 row_ror:12 row_mask:0xf bank_mask:0x5
	v_min_u32_dpp v7, v6, v6 row_ror:4 row_mask:0xf bank_mask:0xa
	s_nop 1
	v_max_u32_dpp v250, v7, v7 quad_perm:[2,3,0,1] row_mask:0xf bank_mask:0xf
	v_min_u32_dpp v251, v7, v7 quad_perm:[2,3,0,1] row_mask:0xf bank_mask:0xf
	v_cndmask_b32_e64 v6, v251, v250, s[48:49]
	s_nop 1
	v_max_u32_dpp v250, v6, v6 quad_perm:[1,0,3,2] row_mask:0xf bank_mask:0xf
	v_min_u32_dpp v251, v6, v6 quad_perm:[1,0,3,2] row_mask:0xf bank_mask:0xf
	v_cndmask_b32_e32 v7, v251, v250, vcc
	v_xor_b32_e32 v253, 63, v81
	v_lshlrev_b32_e32 v253, 2, v253
	ds_bpermute_b32 v252, v253, v7
	s_waitcnt lgkmcnt(0)
	v_max_u32_dpp v6, v252, v7 quad_perm:[0,1,2,3] row_mask:0x3 bank_mask:0xf
	v_min_u32_dpp v6, v252, v7 quad_perm:[0,1,2,3] row_mask:0xc bank_mask:0xf
	ds_swizzle_b32 v252, v6 offset:0x401f
	s_waitcnt lgkmcnt(0)
	v_max_u32_dpp v7, v252, v6 quad_perm:[0,1,2,3] row_mask:0x5 bank_mask:0xf
	v_min_u32_dpp v7, v252, v6 quad_perm:[0,1,2,3] row_mask:0xa bank_mask:0xf
	s_nop 1
	v_max_u32_dpp v6, v7, v7 row_ror:8 row_mask:0xf bank_mask:0x3
	v_min_u32_dpp v6, v7, v7 row_ror:8 row_mask:0xf bank_mask:0xc
	s_nop 1
	v_max_u32_dpp v7, v6, v6 row_ror:12 row_mask:0xf bank_mask:0x5
	v_min_u32_dpp v7, v6, v6 row_ror:4 row_mask:0xf bank_mask:0xa
	s_nop 1
	v_max_u32_dpp v250, v7, v7 quad_perm:[2,3,0,1] row_mask:0xf bank_mask:0xf
	v_min_u32_dpp v251, v7, v7 quad_perm:[2,3,0,1] row_mask:0xf bank_mask:0xf
	v_cndmask_b32_e64 v6, v251, v250, s[48:49]
	s_nop 1
	v_max_u32_dpp v250, v6, v6 quad_perm:[1,0,3,2] row_mask:0xf bank_mask:0xf
	v_min_u32_dpp v251, v6, v6 quad_perm:[1,0,3,2] row_mask:0xf bank_mask:0xf
	v_cndmask_b32_e32 v7, v251, v250, vcc
	v_not_b32_e32 v253, v7
	v_and_b32_e32 v253, 63, v253
	v_lshlrev_b32_e32 v253, 2, v253
	ds_permute_b32 v6, v253, v81
	s_waitcnt lgkmcnt(0)
	v_lshlrev_b32_e32 v8, 3, v6
	v_lshlrev_b32_e32 v7, 7, v6
	v_and_b32_e32 v8, 0x70, v8
	v_and_or_b32 v7, v7, s43, v8
	v_cmp_gt_u32_e32 vcc, 16, v6
	v_and_b32_e32 v8, 0x7f, v31
	s_nop 0
	v_cndmask_b32_e32 v6, 4, v7, vcc
	ds_permute_b32 v0, v6, v0
	v_lshlrev_b32_e32 v7, 7, v23
	v_and_or_b32 v7, v7, s44, v8
	s_waitcnt lgkmcnt(0)
	v_readlane_b32 s2, v0, 0
	s_nop 1
	v_subrev_f32_e32 v0, s2, v0
	v_mul_f32_e32 v0, 0x3fb8aa3b, v0
	v_exp_f32_e32 v0, v0
	v_div_scale_f32 v4, s[2:3], v3, v3, v1
	v_rcp_f32_e32 v5, v4
	v_cndmask_b32_e64 v9, 0, v0, s[12:13]
	s_nop 1
	v_add_f32_dpp v254, v9, v9 quad_perm:[1,0,3,2] row_mask:0xf bank_mask:0xf
	s_nop 1
	v_add_f32_dpp v254, v254, v254 quad_perm:[2,3,0,1] row_mask:0xf bank_mask:0xf
	s_nop 1
	v_add_f32_dpp v254, v254, v254 row_half_mirror row_mask:0xf bank_mask:0xf
	s_nop 1
	v_add_f32_dpp v254, v254, v254 row_mirror row_mask:0xf bank_mask:0xf
	s_nop 1
	v_add_f32_dpp v254, v254, v254 row_bcast:15 row_mask:0xa bank_mask:0xf
	s_nop 1
	v_add_f32_dpp v254, v254, v254 row_bcast:31 row_mask:0xc bank_mask:0xf
	s_nop 1
	v_readlane_b32 s65, v254, 63
	v_fma_f32 v10, -v4, v5, 1.0
	v_fmac_f32_e32 v5, v10, v5
	v_div_scale_f32 v10, vcc, v1, v3, v1
	s_waitcnt lgkmcnt(0)
	v_mul_f32_e32 v12, v10, v5
	v_fma_f32 v13, -v4, v12, v10
	v_fmac_f32_e32 v12, v13, v5
	v_fma_f32 v4, -v4, v12, v10
	s_waitcnt lgkmcnt(0)
	v_div_fmas_f32 v4, v4, v5, v12
	s_waitcnt vmcnt(27)
	v_cmp_lt_i32_e32 vcc, -1, v30
	v_div_fixup_f32 v3, v4, v3, v1
	v_and_b32_e32 v4, 0xffffff80, v22
	v_cndmask_b32_e64 v1, v232, -1, vcc
	v_cmp_lt_i32_e32 vcc, -1, v22
	s_waitcnt lgkmcnt(0)
	v_and_b32_e32 v0, 0xffffff80, v30
	v_cndmask_b32_e64 v5, v232, -1, vcc
	s_waitcnt vmcnt(26)
	v_cmp_lt_i32_e32 vcc, -1, v29
	v_xor_b32_e32 v1, v1, v0
	v_xor_b32_e32 v5, v5, v4
	v_cndmask_b32_e64 v11, v232, -1, vcc
	v_cmp_lt_i32_e32 vcc, -1, v24
	v_and_b32_e32 v0, 0xffffff80, v29
	v_and_b32_e32 v4, 0xffffff80, v24
	v_cndmask_b32_e64 v12, v232, -1, vcc
	v_xor_b32_e32 v0, v11, v0
	v_xor_b32_e32 v4, v12, v4
	v_pk_add_f32 v[0:1], v[4:5], v[0:1]
	v_or_b32_e32 v4, 0x80000000, v1
	v_not_b32_e32 v5, v1
	v_cmp_gt_i32_e32 vcc, 0, v1
	s_nop 1
	v_cndmask_b32_e32 v4, v4, v5, vcc
	v_and_b32_e32 v4, 0xffffffc0, v4
	v_cndmask_b32_e64 v4, 0, v4, s[10:11]
	v_bitop3_b32 v4, v4, 63, v81 bitop3:0x36
	s_nop 0
	s_mov_b32 vcc_lo, 0x55555555
	s_mov_b32 vcc_hi, 0x55555555
	s_mov_b32 s48, 0x33333333
	s_mov_b32 s49, 0x33333333
	v_max_u32_dpp v250, v4, v4 quad_perm:[1,0,3,2] row_mask:0xf bank_mask:0xf
	v_min_u32_dpp v251, v4, v4 quad_perm:[1,0,3,2] row_mask:0xf bank_mask:0xf
	v_cndmask_b32_e32 v5, v251, v250, vcc
	s_nop 1
	v_max_u32_dpp v250, v5, v5 quad_perm:[3,2,1,0] row_mask:0xf bank_mask:0xf
	v_min_u32_dpp v251, v5, v5 quad_perm:[3,2,1,0] row_mask:0xf bank_mask:0xf
	v_cndmask_b32_e64 v4, v251, v250, s[48:49]
	s_nop 1
	v_max_u32_dpp v250, v4, v4 quad_perm:[1,0,3,2] row_mask:0xf bank_mask:0xf
	v_min_u32_dpp v251, v4, v4 quad_perm:[1,0,3,2] row_mask:0xf bank_mask:0xf
	v_cndmask_b32_e32 v5, v251, v250, vcc
	s_nop 1
	v_max_u32_dpp v4, v5, v5 row_half_mirror row_mask:0xf bank_mask:0x5
	v_min_u32_dpp v4, v5, v5 row_half_mirror row_mask:0xf bank_mask:0xa
	s_nop 1
	v_max_u32_dpp v250, v4, v4 quad_perm:[2,3,0,1] row_mask:0xf bank_mask:0xf
	v_min_u32_dpp v251, v4, v4 quad_perm:[2,3,0,1] row_mask:0xf bank_mask:0xf
	v_cndmask_b32_e64 v5, v251, v250, s[48:49]
	s_nop 1
	v_max_u32_dpp v250, v5, v5 quad_perm:[1,0,3,2] row_mask:0xf bank_mask:0xf
	v_min_u32_dpp v251, v5, v5 quad_perm:[1,0,3,2] row_mask:0xf bank_mask:0xf
	v_cndmask_b32_e32 v4, v251, v250, vcc
	s_nop 1
	v_max_u32_dpp v5, v4, v4 row_mirror row_mask:0xf bank_mask:0x3
	v_min_u32_dpp v5, v4, v4 row_mirror row_mask:0xf bank_mask:0xc
	s_nop 1
	v_max_u32_dpp v4, v5, v5 row_ror:12 row_mask:0xf bank_mask:0x5
	v_min_u32_dpp v4, v5, v5 row_ror:4 row_mask:0xf bank_mask:0xa
	s_nop 1
	v_max_u32_dpp v250, v4, v4 quad_perm:[2,3,0,1] row_mask:0xf bank_mask:0xf
	v_min_u32_dpp v251, v4, v4 quad_perm:[2,3,0,1] row_mask:0xf bank_mask:0xf
	v_cndmask_b32_e64 v5, v251, v250, s[48:49]
	s_nop 1
	v_max_u32_dpp v250, v5, v5 quad_perm:[1,0,3,2] row_mask:0xf bank_mask:0xf
	v_min_u32_dpp v251, v5, v5 quad_perm:[1,0,3,2] row_mask:0xf bank_mask:0xf
	v_cndmask_b32_e32 v4, v251, v250, vcc
	ds_swizzle_b32 v252, v4 offset:0x7c1f
	s_waitcnt lgkmcnt(0)
	v_max_u32_dpp v5, v252, v4 quad_perm:[0,1,2,3] row_mask:0x5 bank_mask:0xf
	v_min_u32_dpp v5, v252, v4 quad_perm:[0,1,2,3] row_mask:0xa bank_mask:0xf
	s_nop 1
	v_max_u32_dpp v4, v5, v5 row_ror:8 row_mask:0xf bank_mask:0x3
	v_min_u32_dpp v4, v5, v5 row_ror:8 row_mask:0xf bank_mask:0xc
	s_nop 1
	v_max_u32_dpp v5, v4, v4 row_ror:12 row_mask:0xf bank_mask:0x5
	v_min_u32_dpp v5, v4, v4 row_ror:4 row_mask:0xf bank_mask:0xa
	s_nop 1
	v_max_u32_dpp v250, v5, v5 quad_perm:[2,3,0,1] row_mask:0xf bank_mask:0xf
	v_min_u32_dpp v251, v5, v5 quad_perm:[2,3,0,1] row_mask:0xf bank_mask:0xf
	v_cndmask_b32_e64 v4, v251, v250, s[48:49]
	s_nop 1
	v_max_u32_dpp v250, v4, v4 quad_perm:[1,0,3,2] row_mask:0xf bank_mask:0xf
	v_min_u32_dpp v251, v4, v4 quad_perm:[1,0,3,2] row_mask:0xf bank_mask:0xf
	v_cndmask_b32_e32 v5, v251, v250, vcc
	v_xor_b32_e32 v253, 63, v81
	v_lshlrev_b32_e32 v253, 2, v253
	ds_bpermute_b32 v252, v253, v5
	s_waitcnt lgkmcnt(0)
	v_max_u32_dpp v4, v252, v5 quad_perm:[0,1,2,3] row_mask:0x3 bank_mask:0xf
	v_min_u32_dpp v4, v252, v5 quad_perm:[0,1,2,3] row_mask:0xc bank_mask:0xf
	ds_swizzle_b32 v252, v4 offset:0x401f
	s_waitcnt lgkmcnt(0)
	v_max_u32_dpp v5, v252, v4 quad_perm:[0,1,2,3] row_mask:0x5 bank_mask:0xf
	v_min_u32_dpp v5, v252, v4 quad_perm:[0,1,2,3] row_mask:0xa bank_mask:0xf
	s_nop 1
	v_max_u32_dpp v4, v5, v5 row_ror:8 row_mask:0xf bank_mask:0x3
	v_min_u32_dpp v4, v5, v5 row_ror:8 row_mask:0xf bank_mask:0xc
	s_nop 1
	v_max_u32_dpp v5, v4, v4 row_ror:12 row_mask:0xf bank_mask:0x5
	v_min_u32_dpp v5, v4, v4 row_ror:4 row_mask:0xf bank_mask:0xa
	s_nop 1
	v_max_u32_dpp v250, v5, v5 quad_perm:[2,3,0,1] row_mask:0xf bank_mask:0xf
	v_min_u32_dpp v251, v5, v5 quad_perm:[2,3,0,1] row_mask:0xf bank_mask:0xf
	v_cndmask_b32_e64 v4, v251, v250, s[48:49]
	s_nop 1
	v_max_u32_dpp v250, v4, v4 quad_perm:[1,0,3,2] row_mask:0xf bank_mask:0xf
	v_min_u32_dpp v251, v4, v4 quad_perm:[1,0,3,2] row_mask:0xf bank_mask:0xf
	v_cndmask_b32_e32 v5, v251, v250, vcc
	v_not_b32_e32 v253, v5
	v_and_b32_e32 v253, 63, v253
	v_lshlrev_b32_e32 v253, 2, v253
	ds_permute_b32 v4, v253, v81
	s_waitcnt lgkmcnt(0)
	v_lshlrev_b32_e32 v11, 3, v4
	v_lshlrev_b32_e32 v5, 7, v4
	v_and_b32_e32 v11, 0x70, v11
	v_and_or_b32 v5, v5, s43, v11
	v_cmp_gt_u32_e32 vcc, 16, v4
	ds_permute_b32 v4, v6, v7
	s_nop 0
	v_cndmask_b32_e32 v11, 4, v5, vcc
	ds_permute_b32 v1, v11, v1
	s_waitcnt lgkmcnt(2)
	v_mov_b32_e32 v5, s65
	v_div_scale_f32 v8, s[2:3], v5, v5, v9
	v_rcp_f32_e32 v10, v8
	s_waitcnt lgkmcnt(0)
	v_readlane_b32 s2, v1, 0
	v_div_scale_f32 v7, vcc, v9, v5, v9
	s_nop 0
	v_subrev_f32_e32 v1, s2, v1
	v_mul_f32_e32 v1, 0x3fb8aa3b, v1
	v_exp_f32_e32 v1, v1
	v_fma_f32 v6, -v8, v10, 1.0
	v_fmac_f32_e32 v10, v6, v10
	v_mul_f32_e32 v12, v7, v10
	v_cndmask_b32_e64 v1, 0, v1, s[12:13]
	s_nop 1
	v_add_f32_dpp v254, v1, v1 quad_perm:[1,0,3,2] row_mask:0xf bank_mask:0xf
	s_nop 1
	v_add_f32_dpp v254, v254, v254 quad_perm:[2,3,0,1] row_mask:0xf bank_mask:0xf
	s_nop 1
	v_add_f32_dpp v254, v254, v254 row_half_mirror row_mask:0xf bank_mask:0xf
	s_nop 1
	v_add_f32_dpp v254, v254, v254 row_mirror row_mask:0xf bank_mask:0xf
	s_nop 1
	v_add_f32_dpp v254, v254, v254 row_bcast:15 row_mask:0xa bank_mask:0xf
	s_nop 1
	v_add_f32_dpp v254, v254, v254 row_bcast:31 row_mask:0xc bank_mask:0xf
	s_nop 1
	v_readlane_b32 s64, v254, 63
	v_fma_f32 v13, -v8, v12, v7
	v_fmac_f32_e32 v12, v13, v10
	v_fma_f32 v7, -v8, v12, v7
	v_div_fmas_f32 v7, v7, v10, v12
	s_waitcnt lgkmcnt(0)
	v_div_fixup_f32 v5, v7, v5, v9
	ds_write2st64_b64 v239, v[2:3], v[4:5] offset0:2 offset1:3
	v_not_b32_e32 v7, v0
	v_cmp_gt_i32_e32 vcc, 0, v0
	s_waitcnt lgkmcnt(1)
	v_lshlrev_b32_e32 v2, 7, v22
	v_and_b32_e32 v3, 0x7f, v30
	v_and_or_b32 v2, v2, s44, v3
	v_lshlrev_b32_e32 v3, 7, v24
	s_waitcnt lgkmcnt(0)
	v_or_b32_e32 v6, 0x80000000, v0
	v_cndmask_b32_e32 v6, v6, v7, vcc
	v_and_b32_e32 v6, 0xffffffc0, v6
	v_cndmask_b32_e64 v6, 0, v6, s[10:11]
	v_bitop3_b32 v6, v6, 63, v81 bitop3:0x36
	s_mov_b32 vcc_lo, 0x55555555
	s_waitcnt lgkmcnt(0)
	s_mov_b32 vcc_hi, 0x55555555
	v_mov_b32_e32 v4, s64
	s_mov_b32 s48, 0x33333333
	s_mov_b32 s49, 0x33333333
	v_max_u32_dpp v250, v6, v6 quad_perm:[1,0,3,2] row_mask:0xf bank_mask:0xf
	v_min_u32_dpp v251, v6, v6 quad_perm:[1,0,3,2] row_mask:0xf bank_mask:0xf
	v_cndmask_b32_e32 v7, v251, v250, vcc
	s_nop 1
	v_max_u32_dpp v250, v7, v7 quad_perm:[3,2,1,0] row_mask:0xf bank_mask:0xf
	v_min_u32_dpp v251, v7, v7 quad_perm:[3,2,1,0] row_mask:0xf bank_mask:0xf
	v_cndmask_b32_e64 v6, v251, v250, s[48:49]
	s_nop 1
	v_max_u32_dpp v250, v6, v6 quad_perm:[1,0,3,2] row_mask:0xf bank_mask:0xf
	v_min_u32_dpp v251, v6, v6 quad_perm:[1,0,3,2] row_mask:0xf bank_mask:0xf
	v_cndmask_b32_e32 v7, v251, v250, vcc
	s_nop 1
	v_max_u32_dpp v6, v7, v7 row_half_mirror row_mask:0xf bank_mask:0x5
	v_min_u32_dpp v6, v7, v7 row_half_mirror row_mask:0xf bank_mask:0xa
	s_nop 1
	v_max_u32_dpp v250, v6, v6 quad_perm:[2,3,0,1] row_mask:0xf bank_mask:0xf
	v_min_u32_dpp v251, v6, v6 quad_perm:[2,3,0,1] row_mask:0xf bank_mask:0xf
	v_cndmask_b32_e64 v7, v251, v250, s[48:49]
	s_nop 1
	v_max_u32_dpp v250, v7, v7 quad_perm:[1,0,3,2] row_mask:0xf bank_mask:0xf
	v_min_u32_dpp v251, v7, v7 quad_perm:[1,0,3,2] row_mask:0xf bank_mask:0xf
	v_cndmask_b32_e32 v6, v251, v250, vcc
	s_nop 1
	v_max_u32_dpp v7, v6, v6 row_mirror row_mask:0xf bank_mask:0x3
	v_min_u32_dpp v7, v6, v6 row_mirror row_mask:0xf bank_mask:0xc
	s_nop 1
	v_max_u32_dpp v6, v7, v7 row_ror:12 row_mask:0xf bank_mask:0x5
	v_min_u32_dpp v6, v7, v7 row_ror:4 row_mask:0xf bank_mask:0xa
	s_nop 1
	v_max_u32_dpp v250, v6, v6 quad_perm:[2,3,0,1] row_mask:0xf bank_mask:0xf
	v_min_u32_dpp v251, v6, v6 quad_perm:[2,3,0,1] row_mask:0xf bank_mask:0xf
	v_cndmask_b32_e64 v7, v251, v250, s[48:49]
	s_nop 1
	v_max_u32_dpp v250, v7, v7 quad_perm:[1,0,3,2] row_mask:0xf bank_mask:0xf
	v_min_u32_dpp v251, v7, v7 quad_perm:[1,0,3,2] row_mask:0xf bank_mask:0xf
	v_cndmask_b32_e32 v6, v251, v250, vcc
	ds_swizzle_b32 v252, v6 offset:0x7c1f
	s_waitcnt lgkmcnt(0)
	v_max_u32_dpp v7, v252, v6 quad_perm:[0,1,2,3] row_mask:0x5 bank_mask:0xf
	v_min_u32_dpp v7, v252, v6 quad_perm:[0,1,2,3] row_mask:0xa bank_mask:0xf
	s_nop 1
	v_max_u32_dpp v6, v7, v7 row_ror:8 row_mask:0xf bank_mask:0x3
	v_min_u32_dpp v6, v7, v7 row_ror:8 row_mask:0xf bank_mask:0xc
	s_nop 1
	v_max_u32_dpp v7, v6, v6 row_ror:12 row_mask:0xf bank_mask:0x5
	v_min_u32_dpp v7, v6, v6 row_ror:4 row_mask:0xf bank_mask:0xa
	s_nop 1
	v_max_u32_dpp v250, v7, v7 quad_perm:[2,3,0,1] row_mask:0xf bank_mask:0xf
	v_min_u32_dpp v251, v7, v7 quad_perm:[2,3,0,1] row_mask:0xf bank_mask:0xf
	v_cndmask_b32_e64 v6, v251, v250, s[48:49]
	s_nop 1
	v_max_u32_dpp v250, v6, v6 quad_perm:[1,0,3,2] row_mask:0xf bank_mask:0xf
	v_min_u32_dpp v251, v6, v6 quad_perm:[1,0,3,2] row_mask:0xf bank_mask:0xf
	v_cndmask_b32_e32 v7, v251, v250, vcc
	v_xor_b32_e32 v253, 63, v81
	v_lshlrev_b32_e32 v253, 2, v253
	ds_bpermute_b32 v252, v253, v7
	s_waitcnt lgkmcnt(0)
	v_max_u32_dpp v6, v252, v7 quad_perm:[0,1,2,3] row_mask:0x3 bank_mask:0xf
	v_min_u32_dpp v6, v252, v7 quad_perm:[0,1,2,3] row_mask:0xc bank_mask:0xf
	ds_swizzle_b32 v252, v6 offset:0x401f
	s_waitcnt lgkmcnt(0)
	v_max_u32_dpp v7, v252, v6 quad_perm:[0,1,2,3] row_mask:0x5 bank_mask:0xf
	v_min_u32_dpp v7, v252, v6 quad_perm:[0,1,2,3] row_mask:0xa bank_mask:0xf
	s_nop 1
	v_max_u32_dpp v6, v7, v7 row_ror:8 row_mask:0xf bank_mask:0x3
	v_min_u32_dpp v6, v7, v7 row_ror:8 row_mask:0xf bank_mask:0xc
	s_nop 1
	v_max_u32_dpp v7, v6, v6 row_ror:12 row_mask:0xf bank_mask:0x5
	v_min_u32_dpp v7, v6, v6 row_ror:4 row_mask:0xf bank_mask:0xa
	s_nop 1
	v_max_u32_dpp v250, v7, v7 quad_perm:[2,3,0,1] row_mask:0xf bank_mask:0xf
	v_min_u32_dpp v251, v7, v7 quad_perm:[2,3,0,1] row_mask:0xf bank_mask:0xf
	v_cndmask_b32_e64 v6, v251, v250, s[48:49]
	s_nop 1
	v_max_u32_dpp v250, v6, v6 quad_perm:[1,0,3,2] row_mask:0xf bank_mask:0xf
	v_min_u32_dpp v251, v6, v6 quad_perm:[1,0,3,2] row_mask:0xf bank_mask:0xf
	v_cndmask_b32_e32 v7, v251, v250, vcc
	v_not_b32_e32 v253, v7
	v_and_b32_e32 v253, 63, v253
	v_lshlrev_b32_e32 v253, 2, v253
	ds_permute_b32 v6, v253, v81
	s_waitcnt lgkmcnt(0)
	v_lshlrev_b32_e32 v8, 3, v6
	v_lshlrev_b32_e32 v7, 7, v6
	v_and_b32_e32 v8, 0x70, v8
	v_and_or_b32 v7, v7, s43, v8
	v_cmp_gt_u32_e32 vcc, 16, v6
	s_nop 1
	v_cndmask_b32_e32 v6, 4, v7, vcc
	ds_permute_b32 v0, v6, v0
	v_and_b32_e32 v7, 0x7f, v29
	v_and_or_b32 v7, v3, s44, v7
	s_waitcnt lgkmcnt(0)
	v_readlane_b32 s2, v0, 0
	s_nop 1
	v_subrev_f32_e32 v0, s2, v0
	v_mul_f32_e32 v0, 0x3fb8aa3b, v0
	v_exp_f32_e32 v5, v0
	ds_permute_b32 v0, v11, v2
	v_div_scale_f32 v8, s[2:3], v4, v4, v1
	v_cndmask_b32_e64 v10, 0, v5, s[12:13]
	s_nop 1
	v_add_f32_dpp v254, v10, v10 quad_perm:[1,0,3,2] row_mask:0xf bank_mask:0xf
	s_nop 1
	v_add_f32_dpp v254, v254, v254 quad_perm:[2,3,0,1] row_mask:0xf bank_mask:0xf
	s_nop 1
	v_add_f32_dpp v254, v254, v254 row_half_mirror row_mask:0xf bank_mask:0xf
	s_nop 1
	v_add_f32_dpp v254, v254, v254 row_mirror row_mask:0xf bank_mask:0xf
	s_nop 1
	v_add_f32_dpp v254, v254, v254 row_bcast:15 row_mask:0xa bank_mask:0xf
	s_nop 1
	v_add_f32_dpp v254, v254, v254 row_bcast:31 row_mask:0xc bank_mask:0xf
	s_nop 1
	v_readlane_b32 s65, v254, 63
	v_rcp_f32_e32 v9, v8
	s_waitcnt lgkmcnt(0)
	v_fma_f32 v5, -v8, v9, 1.0
	v_fmac_f32_e32 v9, v5, v9
	v_div_scale_f32 v5, vcc, v1, v4, v1
	v_mul_f32_e32 v12, v5, v9
	v_fma_f32 v13, -v8, v12, v5
	v_fmac_f32_e32 v12, v13, v9
	s_waitcnt lgkmcnt(0)
	v_fma_f32 v5, -v8, v12, v5
	v_div_fmas_f32 v5, v5, v9, v12
	s_waitcnt vmcnt(25)
	v_cmp_lt_i32_e32 vcc, -1, v19
	v_div_fixup_f32 v1, v5, v4, v1
	v_and_b32_e32 v4, 0xffffff80, v20
	v_cndmask_b32_e64 v3, v232, -1, vcc
	v_cmp_lt_i32_e32 vcc, -1, v20
	s_waitcnt lgkmcnt(0)
	v_and_b32_e32 v2, 0xffffff80, v19
	v_cndmask_b32_e64 v5, v232, -1, vcc
	s_waitcnt vmcnt(24)
	v_cmp_lt_i32_e32 vcc, -1, v16
	v_xor_b32_e32 v3, v3, v2
	v_xor_b32_e32 v5, v5, v4
	v_cndmask_b32_e64 v11, v232, -1, vcc
	v_cmp_lt_i32_e32 vcc, -1, v18
	v_and_b32_e32 v2, 0xffffff80, v16
	v_and_b32_e32 v4, 0xffffff80, v18
	v_cndmask_b32_e64 v12, v232, -1, vcc
	v_xor_b32_e32 v2, v11, v2
	v_xor_b32_e32 v4, v12, v4
	v_pk_add_f32 v[2:3], v[4:5], v[2:3]
	v_or_b32_e32 v4, 0x80000000, v3
	v_not_b32_e32 v5, v3
	v_cmp_gt_i32_e32 vcc, 0, v3
	s_nop 1
	v_cndmask_b32_e32 v4, v4, v5, vcc
	v_and_b32_e32 v4, 0xffffffc0, v4
	v_cndmask_b32_e64 v4, 0, v4, s[10:11]
	v_bitop3_b32 v4, v4, 63, v81 bitop3:0x36
	s_nop 0
	s_mov_b32 vcc_lo, 0x55555555
	s_mov_b32 vcc_hi, 0x55555555
	s_mov_b32 s48, 0x33333333
	s_mov_b32 s49, 0x33333333
	v_max_u32_dpp v250, v4, v4 quad_perm:[1,0,3,2] row_mask:0xf bank_mask:0xf
	v_min_u32_dpp v251, v4, v4 quad_perm:[1,0,3,2] row_mask:0xf bank_mask:0xf
	v_cndmask_b32_e32 v5, v251, v250, vcc
	s_nop 1
	v_max_u32_dpp v250, v5, v5 quad_perm:[3,2,1,0] row_mask:0xf bank_mask:0xf
	v_min_u32_dpp v251, v5, v5 quad_perm:[3,2,1,0] row_mask:0xf bank_mask:0xf
	v_cndmask_b32_e64 v4, v251, v250, s[48:49]
	s_nop 1
	v_max_u32_dpp v250, v4, v4 quad_perm:[1,0,3,2] row_mask:0xf bank_mask:0xf
	v_min_u32_dpp v251, v4, v4 quad_perm:[1,0,3,2] row_mask:0xf bank_mask:0xf
	v_cndmask_b32_e32 v5, v251, v250, vcc
	s_nop 1
	v_max_u32_dpp v4, v5, v5 row_half_mirror row_mask:0xf bank_mask:0x5
	v_min_u32_dpp v4, v5, v5 row_half_mirror row_mask:0xf bank_mask:0xa
	s_nop 1
	v_max_u32_dpp v250, v4, v4 quad_perm:[2,3,0,1] row_mask:0xf bank_mask:0xf
	v_min_u32_dpp v251, v4, v4 quad_perm:[2,3,0,1] row_mask:0xf bank_mask:0xf
	v_cndmask_b32_e64 v5, v251, v250, s[48:49]
	s_nop 1
	v_max_u32_dpp v250, v5, v5 quad_perm:[1,0,3,2] row_mask:0xf bank_mask:0xf
	v_min_u32_dpp v251, v5, v5 quad_perm:[1,0,3,2] row_mask:0xf bank_mask:0xf
	v_cndmask_b32_e32 v4, v251, v250, vcc
	s_nop 1
	v_max_u32_dpp v5, v4, v4 row_mirror row_mask:0xf bank_mask:0x3
	v_min_u32_dpp v5, v4, v4 row_mirror row_mask:0xf bank_mask:0xc
	s_nop 1
	v_max_u32_dpp v4, v5, v5 row_ror:12 row_mask:0xf bank_mask:0x5
	v_min_u32_dpp v4, v5, v5 row_ror:4 row_mask:0xf bank_mask:0xa
	s_nop 1
	v_max_u32_dpp v250, v4, v4 quad_perm:[2,3,0,1] row_mask:0xf bank_mask:0xf
	v_min_u32_dpp v251, v4, v4 quad_perm:[2,3,0,1] row_mask:0xf bank_mask:0xf
	v_cndmask_b32_e64 v5, v251, v250, s[48:49]
	s_nop 1
	v_max_u32_dpp v250, v5, v5 quad_perm:[1,0,3,2] row_mask:0xf bank_mask:0xf
	v_min_u32_dpp v251, v5, v5 quad_perm:[1,0,3,2] row_mask:0xf bank_mask:0xf
	v_cndmask_b32_e32 v4, v251, v250, vcc
	ds_swizzle_b32 v252, v4 offset:0x7c1f
	s_waitcnt lgkmcnt(0)
	v_max_u32_dpp v5, v252, v4 quad_perm:[0,1,2,3] row_mask:0x5 bank_mask:0xf
	v_min_u32_dpp v5, v252, v4 quad_perm:[0,1,2,3] row_mask:0xa bank_mask:0xf
	s_nop 1
	v_max_u32_dpp v4, v5, v5 row_ror:8 row_mask:0xf bank_mask:0x3
	v_min_u32_dpp v4, v5, v5 row_ror:8 row_mask:0xf bank_mask:0xc
	s_nop 1
	v_max_u32_dpp v5, v4, v4 row_ror:12 row_mask:0xf bank_mask:0x5
	v_min_u32_dpp v5, v4, v4 row_ror:4 row_mask:0xf bank_mask:0xa
	s_nop 1
	v_max_u32_dpp v250, v5, v5 quad_perm:[2,3,0,1] row_mask:0xf bank_mask:0xf
	v_min_u32_dpp v251, v5, v5 quad_perm:[2,3,0,1] row_mask:0xf bank_mask:0xf
	v_cndmask_b32_e64 v4, v251, v250, s[48:49]
	s_nop 1
	v_max_u32_dpp v250, v4, v4 quad_perm:[1,0,3,2] row_mask:0xf bank_mask:0xf
	v_min_u32_dpp v251, v4, v4 quad_perm:[1,0,3,2] row_mask:0xf bank_mask:0xf
	v_cndmask_b32_e32 v5, v251, v250, vcc
	v_xor_b32_e32 v253, 63, v81
	v_lshlrev_b32_e32 v253, 2, v253
	ds_bpermute_b32 v252, v253, v5
	s_waitcnt lgkmcnt(0)
	v_max_u32_dpp v4, v252, v5 quad_perm:[0,1,2,3] row_mask:0x3 bank_mask:0xf
	v_min_u32_dpp v4, v252, v5 quad_perm:[0,1,2,3] row_mask:0xc bank_mask:0xf
	ds_swizzle_b32 v252, v4 offset:0x401f
	s_waitcnt lgkmcnt(0)
	v_max_u32_dpp v5, v252, v4 quad_perm:[0,1,2,3] row_mask:0x5 bank_mask:0xf
	v_min_u32_dpp v5, v252, v4 quad_perm:[0,1,2,3] row_mask:0xa bank_mask:0xf
	s_nop 1
	v_max_u32_dpp v4, v5, v5 row_ror:8 row_mask:0xf bank_mask:0x3
	v_min_u32_dpp v4, v5, v5 row_ror:8 row_mask:0xf bank_mask:0xc
	s_nop 1
	v_max_u32_dpp v5, v4, v4 row_ror:12 row_mask:0xf bank_mask:0x5
	v_min_u32_dpp v5, v4, v4 row_ror:4 row_mask:0xf bank_mask:0xa
	s_nop 1
	v_max_u32_dpp v250, v5, v5 quad_perm:[2,3,0,1] row_mask:0xf bank_mask:0xf
	v_min_u32_dpp v251, v5, v5 quad_perm:[2,3,0,1] row_mask:0xf bank_mask:0xf
	v_cndmask_b32_e64 v4, v251, v250, s[48:49]
	s_nop 1
	v_max_u32_dpp v250, v4, v4 quad_perm:[1,0,3,2] row_mask:0xf bank_mask:0xf
	v_min_u32_dpp v251, v4, v4 quad_perm:[1,0,3,2] row_mask:0xf bank_mask:0xf
	v_cndmask_b32_e32 v5, v251, v250, vcc
	v_not_b32_e32 v253, v5
	v_and_b32_e32 v253, 63, v253
	v_lshlrev_b32_e32 v253, 2, v253
	ds_permute_b32 v4, v253, v81
	s_waitcnt lgkmcnt(0)
	v_lshlrev_b32_e32 v11, 3, v4
	v_lshlrev_b32_e32 v5, 7, v4
	v_and_b32_e32 v11, 0x70, v11
	v_and_or_b32 v5, v5, s43, v11
	v_cmp_gt_u32_e32 vcc, 16, v4
	ds_permute_b32 v4, v6, v7
	s_nop 0
	v_cndmask_b32_e32 v11, 4, v5, vcc
	s_waitcnt lgkmcnt(1)
	v_mov_b32_e32 v5, s65
	v_div_scale_f32 v8, s[2:3], v5, v5, v10
	v_rcp_f32_e32 v9, v8
	v_div_scale_f32 v7, vcc, v10, v5, v10
	ds_permute_b32 v3, v11, v3
	v_fma_f32 v6, -v8, v9, 1.0
	v_fmac_f32_e32 v9, v6, v9
	v_mul_f32_e32 v12, v7, v9
	v_fma_f32 v13, -v8, v12, v7
	v_fmac_f32_e32 v12, v13, v9
	v_fma_f32 v7, -v8, v12, v7
	v_div_fmas_f32 v7, v7, v9, v12
	v_or_b32_e32 v8, 0x80000000, v2
	v_not_b32_e32 v9, v2
	v_cmp_gt_i32_e32 vcc, 0, v2
	s_waitcnt lgkmcnt(0)
	v_readlane_b32 s2, v3, 0
	v_div_fixup_f32 v5, v7, v5, v10
	v_cndmask_b32_e32 v8, v8, v9, vcc
	v_and_b32_e32 v8, 0xffffffc0, v8
	v_cndmask_b32_e64 v8, 0, v8, s[10:11]
	v_bitop3_b32 v8, v8, 63, v81 bitop3:0x36
	v_subrev_f32_e32 v3, s2, v3
	s_mov_b32 vcc_lo, 0x55555555
	v_mul_f32_e32 v3, 0x3fb8aa3b, v3
	v_exp_f32_e32 v3, v3
	s_mov_b32 vcc_hi, 0x55555555
	s_mov_b32 s48, 0x33333333
	s_mov_b32 s49, 0x33333333
	ds_write2st64_b64 v239, v[0:1], v[4:5] offset0:4 offset1:5
	v_max_u32_dpp v250, v8, v8 quad_perm:[1,0,3,2] row_mask:0xf bank_mask:0xf
	v_min_u32_dpp v251, v8, v8 quad_perm:[1,0,3,2] row_mask:0xf bank_mask:0xf
	v_cndmask_b32_e32 v9, v251, v250, vcc
	v_cndmask_b32_e64 v3, 0, v3, s[12:13]
	s_nop 1
	v_add_f32_dpp v254, v3, v3 quad_perm:[1,0,3,2] row_mask:0xf bank_mask:0xf
	s_nop 1
	v_add_f32_dpp v254, v254, v254 quad_perm:[2,3,0,1] row_mask:0xf bank_mask:0xf
	s_nop 1
	v_add_f32_dpp v254, v254, v254 row_half_mirror row_mask:0xf bank_mask:0xf
	s_nop 1
	v_add_f32_dpp v254, v254, v254 row_mirror row_mask:0xf bank_mask:0xf
	s_nop 1
	v_add_f32_dpp v254, v254, v254 row_bcast:15 row_mask:0xa bank_mask:0xf
	s_nop 1
	v_add_f32_dpp v254, v254, v254 row_bcast:31 row_mask:0xc bank_mask:0xf
	s_nop 1
	v_readlane_b32 s64, v254, 63
	s_nop 1
	v_max_u32_dpp v250, v9, v9 quad_perm:[3,2,1,0] row_mask:0xf bank_mask:0xf
	v_min_u32_dpp v251, v9, v9 quad_perm:[3,2,1,0] row_mask:0xf bank_mask:0xf
	v_cndmask_b32_e64 v8, v251, v250, s[48:49]
	s_nop 1
	v_max_u32_dpp v250, v8, v8 quad_perm:[1,0,3,2] row_mask:0xf bank_mask:0xf
	v_lshlrev_b32_e32 v0, 7, v20
	v_min_u32_dpp v251, v8, v8 quad_perm:[1,0,3,2] row_mask:0xf bank_mask:0xf
	v_cndmask_b32_e32 v9, v251, v250, vcc
	s_nop 1
	s_waitcnt lgkmcnt(0)
	v_max_u32_dpp v8, v9, v9 row_half_mirror row_mask:0xf bank_mask:0x5
	v_min_u32_dpp v8, v9, v9 row_half_mirror row_mask:0xf bank_mask:0xa
	s_nop 1
	v_max_u32_dpp v250, v8, v8 quad_perm:[2,3,0,1] row_mask:0xf bank_mask:0xf
	v_min_u32_dpp v251, v8, v8 quad_perm:[2,3,0,1] row_mask:0xf bank_mask:0xf
	v_cndmask_b32_e64 v9, v251, v250, s[48:49]
	s_waitcnt lgkmcnt(0)
	s_nop 1
	v_max_u32_dpp v250, v9, v9 quad_perm:[1,0,3,2] row_mask:0xf bank_mask:0xf
	v_min_u32_dpp v251, v9, v9 quad_perm:[1,0,3,2] row_mask:0xf bank_mask:0xf
	v_cndmask_b32_e32 v8, v251, v250, vcc
	s_nop 1
	v_max_u32_dpp v9, v8, v8 row_mirror row_mask:0xf bank_mask:0x3
	v_min_u32_dpp v9, v8, v8 row_mirror row_mask:0xf bank_mask:0xc
	v_and_b32_e32 v1, 0x7f, v19
	s_nop 1
	v_max_u32_dpp v8, v9, v9 row_ror:12 row_mask:0xf bank_mask:0x5
	v_min_u32_dpp v8, v9, v9 row_ror:4 row_mask:0xf bank_mask:0xa
	s_waitcnt lgkmcnt(0)
	s_nop 1
	v_max_u32_dpp v250, v8, v8 quad_perm:[2,3,0,1] row_mask:0xf bank_mask:0xf
	v_min_u32_dpp v251, v8, v8 quad_perm:[2,3,0,1] row_mask:0xf bank_mask:0xf
	v_cndmask_b32_e64 v9, v251, v250, s[48:49]
	v_and_or_b32 v0, v0, s44, v1
	s_nop 1
	v_max_u32_dpp v250, v9, v9 quad_perm:[1,0,3,2] row_mask:0xf bank_mask:0xf
	v_min_u32_dpp v251, v9, v9 quad_perm:[1,0,3,2] row_mask:0xf bank_mask:0xf
	v_cndmask_b32_e32 v8, v251, v250, vcc
	ds_swizzle_b32 v252, v8 offset:0x7c1f
	s_waitcnt lgkmcnt(0)
	ds_permute_b32 v0, v11, v0
	v_max_u32_dpp v9, v252, v8 quad_perm:[0,1,2,3] row_mask:0x5 bank_mask:0xf
	v_min_u32_dpp v9, v252, v8 quad_perm:[0,1,2,3] row_mask:0xa bank_mask:0xf
	v_lshlrev_b32_e32 v6, 7, v18
	s_nop 1
	v_max_u32_dpp v8, v9, v9 row_ror:8 row_mask:0xf bank_mask:0x3
	v_min_u32_dpp v8, v9, v9 row_ror:8 row_mask:0xf bank_mask:0xc
	s_nop 1
	v_max_u32_dpp v9, v8, v8 row_ror:12 row_mask:0xf bank_mask:0x5
	v_min_u32_dpp v9, v8, v8 row_ror:4 row_mask:0xf bank_mask:0xa
	s_nop 1
	v_max_u32_dpp v250, v9, v9 quad_perm:[2,3,0,1] row_mask:0xf bank_mask:0xf
	v_min_u32_dpp v251, v9, v9 quad_perm:[2,3,0,1] row_mask:0xf bank_mask:0xf
	v_cndmask_b32_e64 v8, v251, v250, s[48:49]
	s_nop 1
	v_max_u32_dpp v250, v8, v8 quad_perm:[1,0,3,2] row_mask:0xf bank_mask:0xf
	v_min_u32_dpp v251, v8, v8 quad_perm:[1,0,3,2] row_mask:0xf bank_mask:0xf
	v_cndmask_b32_e32 v9, v251, v250, vcc
	v_xor_b32_e32 v253, 63, v81
	v_lshlrev_b32_e32 v253, 2, v253
	ds_bpermute_b32 v252, v253, v9
	s_waitcnt lgkmcnt(0)
	v_max_u32_dpp v8, v252, v9 quad_perm:[0,1,2,3] row_mask:0x3 bank_mask:0xf
	v_min_u32_dpp v8, v252, v9 quad_perm:[0,1,2,3] row_mask:0xc bank_mask:0xf
	ds_swizzle_b32 v252, v8 offset:0x401f
	s_waitcnt lgkmcnt(0)
	v_max_u32_dpp v9, v252, v8 quad_perm:[0,1,2,3] row_mask:0x5 bank_mask:0xf
	v_min_u32_dpp v9, v252, v8 quad_perm:[0,1,2,3] row_mask:0xa bank_mask:0xf
	s_nop 1
	v_max_u32_dpp v8, v9, v9 row_ror:8 row_mask:0xf bank_mask:0x3
	v_min_u32_dpp v8, v9, v9 row_ror:8 row_mask:0xf bank_mask:0xc
	s_nop 1
	v_max_u32_dpp v9, v8, v8 row_ror:12 row_mask:0xf bank_mask:0x5
	v_min_u32_dpp v9, v8, v8 row_ror:4 row_mask:0xf bank_mask:0xa
	s_nop 1
	v_max_u32_dpp v250, v9, v9 quad_perm:[2,3,0,1] row_mask:0xf bank_mask:0xf
	v_min_u32_dpp v251, v9, v9 quad_perm:[2,3,0,1] row_mask:0xf bank_mask:0xf
	v_cndmask_b32_e64 v8, v251, v250, s[48:49]
	s_nop 1
	v_max_u32_dpp v250, v8, v8 quad_perm:[1,0,3,2] row_mask:0xf bank_mask:0xf
	v_min_u32_dpp v251, v8, v8 quad_perm:[1,0,3,2] row_mask:0xf bank_mask:0xf
	v_cndmask_b32_e32 v9, v251, v250, vcc
	v_not_b32_e32 v253, v9
	v_and_b32_e32 v253, 63, v253
	v_lshlrev_b32_e32 v253, 2, v253
	ds_permute_b32 v8, v253, v81
	s_waitcnt lgkmcnt(0)
	v_lshlrev_b32_e32 v10, 3, v8
	v_lshlrev_b32_e32 v9, 7, v8
	v_and_b32_e32 v10, 0x70, v10
	v_and_or_b32 v9, v9, s43, v10
	v_cmp_gt_u32_e32 vcc, 16, v8
	v_and_b32_e32 v10, 0x7f, v16
	s_nop 0
	v_cndmask_b32_e32 v8, 4, v9, vcc
	ds_permute_b32 v2, v8, v2
	s_waitcnt lgkmcnt(0)
	v_readlane_b32 s2, v2, 0
	s_nop 1
	v_subrev_f32_e32 v2, s2, v2
	v_mul_f32_e32 v2, 0x3fb8aa3b, v2
	v_exp_f32_e32 v2, v2
	s_nop 0
	v_cndmask_b32_e64 v7, 0, v2, s[12:13]
	s_nop 1
	v_add_f32_dpp v254, v7, v7 quad_perm:[1,0,3,2] row_mask:0xf bank_mask:0xf
	s_nop 1
	v_add_f32_dpp v254, v254, v254 quad_perm:[2,3,0,1] row_mask:0xf bank_mask:0xf
	s_nop 1
	v_add_f32_dpp v254, v254, v254 row_half_mirror row_mask:0xf bank_mask:0xf
	s_nop 1
	v_add_f32_dpp v254, v254, v254 row_mirror row_mask:0xf bank_mask:0xf
	s_nop 1
	v_add_f32_dpp v254, v254, v254 row_bcast:15 row_mask:0xa bank_mask:0xf
	s_nop 1
	v_add_f32_dpp v254, v254, v254 row_bcast:31 row_mask:0xc bank_mask:0xf
	s_nop 1
	v_readlane_b32 s65, v254, 63
	v_mov_b32_e32 v2, s64
	v_div_scale_f32 v4, s[2:3], v2, v2, v3
	v_rcp_f32_e32 v5, v4
	s_waitcnt lgkmcnt(0)
	v_fma_f32 v11, -v4, v5, 1.0
	v_fmac_f32_e32 v5, v11, v5
	v_div_scale_f32 v11, vcc, v3, v2, v3
	s_waitcnt lgkmcnt(0)
	v_mul_f32_e32 v12, v11, v5
	v_fma_f32 v13, -v4, v12, v11
	v_fmac_f32_e32 v12, v13, v5
	v_fma_f32 v4, -v4, v12, v11
	s_waitcnt lgkmcnt(0)
	v_div_fmas_f32 v4, v4, v5, v12
	s_waitcnt lgkmcnt(0)
	v_mov_b32_e32 v5, s65
	v_div_scale_f32 v9, s[2:3], v5, v5, v7
	v_rcp_f32_e32 v11, v9
	v_div_fixup_f32 v1, v4, v2, v3
	v_and_or_b32 v2, v6, s44, v10
	ds_permute_b32 v2, v8, v2
	v_fma_f32 v3, -v9, v11, 1.0
	v_fmac_f32_e32 v11, v3, v11
	v_div_scale_f32 v3, vcc, v7, v5, v7
	v_mul_f32_e32 v4, v3, v11
	v_fma_f32 v6, -v9, v4, v3
	v_fmac_f32_e32 v4, v6, v11
	v_fma_f32 v3, -v9, v4, v3
	v_div_fmas_f32 v3, v3, v11, v4
	v_div_fixup_f32 v3, v3, v5, v7
	s_waitcnt lgkmcnt(0)
	ds_write2st64_b64 v239, v[0:1], v[2:3] offset0:6 offset1:7
	s_branch .LBB0_330
